# attention loop headers aligned to 64 bytes; global_* ops, deferred SSQ atomics
# baseline (speedup 1.0000x reference)
;   #define RESC() do{ if constexpr(!FIXED) if(resc){ asm volatile("s_waitcnt lgkmcnt(0)":::"memory"); \
;       _Pragma("unroll") for(int d_=0;d_<4;++d_) _Pragma("unroll") for(int r=0;r<16;++r)o[d_][r]*=wsf[crow(r,hi)]; } }while(0)
;   #define ROT() do{sl_prev=sl_cur;sl_cur=sl_next;sl_next=(sl_next==(NSLOT-1)*SLOTB)?0:sl_next+SLOTB;}while(0)
;   #define ENDW(tt) do{ if((tt)+3<NT){WAIT_BAR(3);} else if((tt)+2<NT){WAIT_BAR(2);} else {WAIT_BAR(0);} }while(0)
; template<int THRL,bool FIXED> __device__ __forceinline__ void attn_unit(int qb,const bf16*Q,const bf16*__restrict__ Kh,const bf16*__restrict__ Vh,bf16*O,const int*__restrict__ cid,char*shm,const int wid){
;     ...
;   for(;t+1<NT;t+=2){
;     STEP(pB0,pB1,pA0,pA1,t,(t+3<NT),(t+1<NT),(t+1<NT));       ENDW(t);   RESC(); ROT();
;     STEP(pA0,pA1,pB0,pB1,t+1,(t+4<NT),(t+2<NT),(t+2<NT));     ENDW(t+1); RESC(); ROT();
;   }
.LBB0_1069:
.LBB0_1070:
	s_add_i32 s30, s13, -2
	s_add_i32 s56, s10, 2
	s_lshl_b64 s[4:5], s[10:11], 17
	v_readlane_b32 s0, v254, 8
	s_add_u32 s0, s0, s52
	v_readlane_b32 s1, v254, 9
	s_addc_u32 s1, s1, s53
	v_lshl_add_u32 v68, s10, 8, v67
	v_lshl_add_u64 v[224:225], s[0:1], 0, v[210:211]
	s_lshl_b32 s0, s13, 8
	v_subrev_u32_e32 v68, s0, v68
	v_readlane_b32 s0, v254, 14
	s_sub_i32 s31, 0, s13
	v_readlane_b32 s1, v254, 13
	v_add_u32_e32 v241, s0, v68
	v_readlane_b32 s0, v254, 12
	s_add_u32 s0, s0, s50
	v_lshl_add_u64 v[68:69], v[212:213], 0, v[0:1]
	s_addc_u32 s1, s1, s51
	v_lshl_add_u64 v[226:227], s[0:1], 0, v[68:69]
	.p2alignl 6, 3212836864
